# v181 plus P3 epilogue with coalesced gate and partial loads and merged stores through the per-wave LDS tile
# baseline (speedup 1.0000x reference)
; __device__ __forceinline__ void unpack8(const u32x4 w, float (&f)[8]) { f[0] = bflo(w.x); f[1] = bfhi(w.x); f[2] = bflo(w.y); f[3] = bfhi(w.y); f[4] = bflo(w.z); f[5] = bfhi(w.z); f[6] = bflo(w.w); f[7] = bfhi(w.w); }
; __device__ __forceinline__ u32x4 pack8(const float (&f)[8]) { u32x4 w; w.x = cvt_pk_bf16(f[0], f[1]); w.y = cvt_pk_bf16(f[2], f[3]); w.z = cvt_pk_bf16(f[4], f[5]); w.w = cvt_pk_bf16(f[6], f[7]); return w; }
;     __device__ __forceinline__ void operator()(const f32x4 (&acc)[2][2][4][2], const Unit& u, int wr, int wc, int fr, int fq) const {
;         const int row0 = u.pm * BM + wr * 64 + fr, col0 = u.pn * BM + wc * 32 + 8 * fq;
; #pragma unroll
;         for (int ai = 0; ai < 2; ++ai)
; #pragma unroll
;             for (int m = 0; m < 4; ++m) { const size_t idx = (size_t)(row0 + ai * HALF + m * 16) * 1024 + col0;
; #pragma unroll
;                 for (int bj = 0; bj < 2; ++bj) { const f32x4 v0 = acc[ai][bj][m][0], v1 = acc[ai][bj][m][1];
;                     float f[8] = {v0[0], v0[1], v0[2], v0[3], v1[0], v1[1], v1[2], v1[3]}; float g[8];
;                     unpack8(__builtin_nontemporal_load((const u32x4*)(gate + idx + bj * HALF)), g);
; #pragma unroll
;                     for (int e = 0; e < 8; ++e) f[e] *= g[e];
;                     if (!FIRST) { float p[8]; unpack8(*(const u32x4*)(merged + idx + bj * HALF), p);
; #pragma unroll
;                         for (int e = 0; e < 8; ++e) f[e] += p[e]; }
;                     *(u32x4*)(merged + idx + bj * HALF) = pack8(f); } }
;     __device__ __forceinline__ void operator()(const f32x4 (&acc)[2][2][4][2], const Unit& u, int wr, int wc, int fr, int fq) const {
;         if (u.pm < 128) e0(acc, u, wr, wc, fr, fq); else { const Unit v{u.pm - 128, u.pn - 4}; e1(acc, v, wr, wc, fr, fq); }
.LBB0_566:
	s_and_b32 s98, s44, 0x7f
	s_and_b32 s99, s45, 3
	s_cmpk_gt_i32 s44, 0x7f
	s_cselect_b32 s100, s14, s12
	s_cselect_b32 s101, s15, s13
	v_mbcnt_lo_u32_b32 v235, -1, 0
	v_mbcnt_hi_u32_b32 v235, -1, v235
	v_lshrrev_b32_e32 v236, 2, v235
	v_and_b32_e32 v237, 3, v235
	v_bfe_u32 v245, v152, 6, 1
	v_bfe_u32 v234, v154, 5, 2
	v_lshl_or_b32 v245, v245, 2, v234
	v_mul_u32_u24_e32 v245, 0x500, v245
	v_add_u32_e32 v244, 0x20000, v245
	v_mul_u32_u24_e32 v234, 0x50, v236
	v_lshl_add_u32 v234, v237, 4, v234
	v_add_u32_e32 v234, v234, v244
	v_and_b32_e32 v245, 15, v152
	v_mul_u32_u24_e32 v245, 0x50, v245
	v_bfe_u32 v242, v154, 3, 2
	v_lshl_add_u32 v245, v242, 4, v245
	v_add_u32_e32 v245, v245, v244
	v_and_or_b32 v244, v152, -16, v236
	v_lshlrev_b32_e32 v237, 3, v237
	v_and_b32_e32 v242, 0xffffffe7, v154
	v_or_b32_e32 v242, v242, v237
	v_lshl_add_u32 v244, s98, 8, v244
	v_lshl_or_b32 v242, s99, 8, v242
	v_lshl_add_u32 v244, v244, 10, v242
	v_lshlrev_b32_e32 v244, 1, v244
	v_mov_b32_e32 v242, v244
	v_mov_b32_e32 v243, v244
	s_cbranch_scc1 .Lp3_second
	global_load_dwordx4 v[160:163], v244, s[100:101] nt
	global_load_dwordx4 v[164:167], v244, s[100:101] offset:256 nt
	v_add_u32_e32 v244, 0x8000, v244
	global_load_dwordx4 v[168:171], v244, s[100:101] nt
	global_load_dwordx4 v[172:175], v244, s[100:101] offset:256 nt
	v_add_u32_e32 v244, 0x8000, v244
	global_load_dwordx4 v[176:179], v244, s[100:101] nt
	global_load_dwordx4 v[180:183], v244, s[100:101] offset:256 nt
	v_add_u32_e32 v244, 0x8000, v244
	global_load_dwordx4 v[184:187], v244, s[100:101] nt
	global_load_dwordx4 v[188:191], v244, s[100:101] offset:256 nt
	v_add_u32_e32 v244, 0x28000, v244
	global_load_dwordx4 v[192:195], v244, s[100:101] nt
	global_load_dwordx4 v[196:199], v244, s[100:101] offset:256 nt
	v_add_u32_e32 v244, 0x8000, v244
	global_load_dwordx4 v[206:209], v244, s[100:101] nt
	global_load_dwordx4 v[210:213], v244, s[100:101] offset:256 nt
	v_add_u32_e32 v244, 0x8000, v244
	global_load_dwordx4 v[214:217], v244, s[100:101] nt
	global_load_dwordx4 v[218:221], v244, s[100:101] offset:256 nt
	v_add_u32_e32 v244, 0x8000, v244
	global_load_dwordx4 v[222:225], v244, s[100:101] nt
	global_load_dwordx4 v[226:229], v244, s[100:101] offset:256 nt
	s_waitcnt vmcnt(14)
	ds_write_b128 v234, v[160:163]
	ds_read_b128 v[160:163], v245
	ds_write_b128 v234, v[164:167]
	ds_read_b128 v[164:167], v245
	s_waitcnt lgkmcnt(0)
	v_lshlrev_b32_e32 v128, 16, v160
	v_and_b32_e32 v129, 0xffff0000, v160
	v_lshlrev_b32_e32 v130, 16, v161
	v_and_b32_e32 v131, 0xffff0000, v161
	v_lshlrev_b32_e32 v230, 16, v162
	v_and_b32_e32 v231, 0xffff0000, v162
	v_lshlrev_b32_e32 v232, 16, v163
	v_and_b32_e32 v233, 0xffff0000, v163
	v_mul_f32_e32 v124, v124, v128
	v_mul_f32_e32 v125, v125, v129
	v_mul_f32_e32 v126, v126, v130
	v_mul_f32_e32 v127, v127, v131
	v_mul_f32_e32 v120, v120, v230
	v_mul_f32_e32 v121, v121, v231
	v_mul_f32_e32 v122, v122, v232
	v_mul_f32_e32 v123, v123, v233
	v_cvt_pk_bf16_f32 v160, v124, v125
	v_cvt_pk_bf16_f32 v161, v126, v127
	v_cvt_pk_bf16_f32 v162, v120, v121
	v_cvt_pk_bf16_f32 v163, v122, v123
	v_lshlrev_b32_e32 v128, 16, v164
	v_and_b32_e32 v129, 0xffff0000, v164
	v_lshlrev_b32_e32 v130, 16, v165
	v_and_b32_e32 v131, 0xffff0000, v165
	v_lshlrev_b32_e32 v230, 16, v166
	v_and_b32_e32 v231, 0xffff0000, v166
	v_lshlrev_b32_e32 v232, 16, v167
	v_and_b32_e32 v233, 0xffff0000, v167
	v_mul_f32_e32 v112, v112, v128
	v_mul_f32_e32 v113, v113, v129
	v_mul_f32_e32 v114, v114, v130
	v_mul_f32_e32 v115, v115, v131
	v_mul_f32_e32 v104, v104, v230
	v_mul_f32_e32 v105, v105, v231
	v_mul_f32_e32 v106, v106, v232
	v_mul_f32_e32 v107, v107, v233
	v_cvt_pk_bf16_f32 v164, v112, v113
	v_cvt_pk_bf16_f32 v165, v114, v115
	v_cvt_pk_bf16_f32 v166, v104, v105
	v_cvt_pk_bf16_f32 v167, v106, v107
	ds_write_b128 v245, v[160:163]
	ds_read_b128 v[160:163], v234
	ds_write_b128 v245, v[164:167]
	ds_read_b128 v[164:167], v234
	s_waitcnt lgkmcnt(2)
	global_store_dwordx4 v243, v[160:163], s[10:11]
	s_waitcnt lgkmcnt(0)
	global_store_dwordx4 v243, v[164:167], s[10:11] offset:256
	v_add_u32_e32 v243, 0x8000, v243
	s_waitcnt vmcnt(14)
	ds_write_b128 v234, v[168:171]
	ds_read_b128 v[168:171], v245
	ds_write_b128 v234, v[172:175]
	ds_read_b128 v[172:175], v245
	s_waitcnt lgkmcnt(0)
	v_lshlrev_b32_e32 v128, 16, v168
	v_and_b32_e32 v129, 0xffff0000, v168
	v_lshlrev_b32_e32 v130, 16, v169
	v_and_b32_e32 v131, 0xffff0000, v169
	v_lshlrev_b32_e32 v230, 16, v170
	v_and_b32_e32 v231, 0xffff0000, v170
	v_lshlrev_b32_e32 v232, 16, v171
	v_and_b32_e32 v233, 0xffff0000, v171
	v_mul_f32_e32 v116, v116, v128
	v_mul_f32_e32 v117, v117, v129
	v_mul_f32_e32 v118, v118, v130
	v_mul_f32_e32 v119, v119, v131
	v_mul_f32_e32 v108, v108, v230
	v_mul_f32_e32 v109, v109, v231
	v_mul_f32_e32 v110, v110, v232
	v_mul_f32_e32 v111, v111, v233
	v_cvt_pk_bf16_f32 v168, v116, v117
	v_cvt_pk_bf16_f32 v169, v118, v119
	v_cvt_pk_bf16_f32 v170, v108, v109
	v_cvt_pk_bf16_f32 v171, v110, v111
	v_lshlrev_b32_e32 v128, 16, v172
	v_and_b32_e32 v129, 0xffff0000, v172
	v_lshlrev_b32_e32 v130, 16, v173
	v_and_b32_e32 v131, 0xffff0000, v173
	v_lshlrev_b32_e32 v230, 16, v174
	v_and_b32_e32 v231, 0xffff0000, v174
	v_lshlrev_b32_e32 v232, 16, v175
	v_and_b32_e32 v233, 0xffff0000, v175
	v_mul_f32_e32 v96, v96, v128
	v_mul_f32_e32 v97, v97, v129
	v_mul_f32_e32 v98, v98, v130
	v_mul_f32_e32 v99, v99, v131
	v_mul_f32_e32 v88, v88, v230
	v_mul_f32_e32 v89, v89, v231
	v_mul_f32_e32 v90, v90, v232
	v_mul_f32_e32 v91, v91, v233
	v_cvt_pk_bf16_f32 v172, v96, v97
	v_cvt_pk_bf16_f32 v173, v98, v99
	v_cvt_pk_bf16_f32 v174, v88, v89
	v_cvt_pk_bf16_f32 v175, v90, v91
	ds_write_b128 v245, v[168:171]
	ds_read_b128 v[168:171], v234
	ds_write_b128 v245, v[172:175]
	ds_read_b128 v[172:175], v234
	s_waitcnt lgkmcnt(2)
; __device__ __forceinline__ void unpack8(const u32x4 w, float (&f)[8]) { f[0] = bflo(w.x); f[1] = bfhi(w.x); f[2] = bflo(w.y); f[3] = bfhi(w.y); f[4] = bflo(w.z); f[5] = bfhi(w.z); f[6] = bflo(w.w); f[7] = bfhi(w.w); }
; __device__ __forceinline__ u32x4 pack8(const float (&f)[8]) { u32x4 w; w.x = cvt_pk_bf16(f[0], f[1]); w.y = cvt_pk_bf16(f[2], f[3]); w.z = cvt_pk_bf16(f[4], f[5]); w.w = cvt_pk_bf16(f[6], f[7]); return w; }
;     __device__ __forceinline__ void operator()(const f32x4 (&acc)[2][2][4][2], const Unit& u, int wr, int wc, int fr, int fq) const {
;         const int row0 = u.pm * BM + wr * 64 + fr, col0 = u.pn * BM + wc * 32 + 8 * fq;
; #pragma unroll
;         for (int ai = 0; ai < 2; ++ai)
; #pragma unroll
;             for (int m = 0; m < 4; ++m) { const size_t idx = (size_t)(row0 + ai * HALF + m * 16) * 1024 + col0;
; #pragma unroll
;                 for (int bj = 0; bj < 2; ++bj) { const f32x4 v0 = acc[ai][bj][m][0], v1 = acc[ai][bj][m][1];
;                     float f[8] = {v0[0], v0[1], v0[2], v0[3], v1[0], v1[1], v1[2], v1[3]}; float g[8];
;                     unpack8(__builtin_nontemporal_load((const u32x4*)(gate + idx + bj * HALF)), g);
; #pragma unroll
;                     for (int e = 0; e < 8; ++e) f[e] *= g[e];
;                     if (!FIRST) { float p[8]; unpack8(*(const u32x4*)(merged + idx + bj * HALF), p);
; #pragma unroll
;                         for (int e = 0; e < 8; ++e) f[e] += p[e]; }
;                     *(u32x4*)(merged + idx + bj * HALF) = pack8(f); } }
	global_store_dwordx4 v243, v[168:171], s[10:11]
	s_waitcnt lgkmcnt(0)
	global_store_dwordx4 v243, v[172:175], s[10:11] offset:256
	v_add_u32_e32 v243, 0x8000, v243
	s_waitcnt vmcnt(14)
	ds_write_b128 v234, v[176:179]
	ds_read_b128 v[176:179], v245
	ds_write_b128 v234, v[180:183]
	ds_read_b128 v[180:183], v245
	s_waitcnt lgkmcnt(0)
	v_lshlrev_b32_e32 v128, 16, v176
	v_and_b32_e32 v129, 0xffff0000, v176
	v_lshlrev_b32_e32 v130, 16, v177
	v_and_b32_e32 v131, 0xffff0000, v177
	v_lshlrev_b32_e32 v230, 16, v178
	v_and_b32_e32 v231, 0xffff0000, v178
	v_lshlrev_b32_e32 v232, 16, v179
	v_and_b32_e32 v233, 0xffff0000, v179
	v_mul_f32_e32 v100, v100, v128
	v_mul_f32_e32 v101, v101, v129
	v_mul_f32_e32 v102, v102, v130
	v_mul_f32_e32 v103, v103, v131
	v_mul_f32_e32 v92, v92, v230
	v_mul_f32_e32 v93, v93, v231
	v_mul_f32_e32 v94, v94, v232
	v_mul_f32_e32 v95, v95, v233
	v_cvt_pk_bf16_f32 v176, v100, v101
	v_cvt_pk_bf16_f32 v177, v102, v103
	v_cvt_pk_bf16_f32 v178, v92, v93
	v_cvt_pk_bf16_f32 v179, v94, v95
	v_lshlrev_b32_e32 v128, 16, v180
	v_and_b32_e32 v129, 0xffff0000, v180
	v_lshlrev_b32_e32 v130, 16, v181
	v_and_b32_e32 v131, 0xffff0000, v181
	v_lshlrev_b32_e32 v230, 16, v182
	v_and_b32_e32 v231, 0xffff0000, v182
	v_lshlrev_b32_e32 v232, 16, v183
	v_and_b32_e32 v233, 0xffff0000, v183
	v_mul_f32_e32 v80, v80, v128
	v_mul_f32_e32 v81, v81, v129
	v_mul_f32_e32 v82, v82, v130
	v_mul_f32_e32 v83, v83, v131
	v_mul_f32_e32 v72, v72, v230
	v_mul_f32_e32 v73, v73, v231
	v_mul_f32_e32 v74, v74, v232
	v_mul_f32_e32 v75, v75, v233
	v_cvt_pk_bf16_f32 v180, v80, v81
	v_cvt_pk_bf16_f32 v181, v82, v83
	v_cvt_pk_bf16_f32 v182, v72, v73
	v_cvt_pk_bf16_f32 v183, v74, v75
	ds_write_b128 v245, v[176:179]
	ds_read_b128 v[176:179], v234
	ds_write_b128 v245, v[180:183]
	ds_read_b128 v[180:183], v234
	s_waitcnt lgkmcnt(2)
	global_store_dwordx4 v243, v[176:179], s[10:11]
	s_waitcnt lgkmcnt(0)
	global_store_dwordx4 v243, v[180:183], s[10:11] offset:256
	v_add_u32_e32 v243, 0x8000, v243
	s_waitcnt vmcnt(14)
	ds_write_b128 v234, v[184:187]
	ds_read_b128 v[184:187], v245
	ds_write_b128 v234, v[188:191]
	ds_read_b128 v[188:191], v245
	s_waitcnt lgkmcnt(0)
	v_lshlrev_b32_e32 v128, 16, v184
	v_and_b32_e32 v129, 0xffff0000, v184
	v_lshlrev_b32_e32 v130, 16, v185
	v_and_b32_e32 v131, 0xffff0000, v185
	v_lshlrev_b32_e32 v230, 16, v186
	v_and_b32_e32 v231, 0xffff0000, v186
	v_lshlrev_b32_e32 v232, 16, v187
	v_and_b32_e32 v233, 0xffff0000, v187
	v_mul_f32_e32 v84, v84, v128
	v_mul_f32_e32 v85, v85, v129
	v_mul_f32_e32 v86, v86, v130
	v_mul_f32_e32 v87, v87, v131
	v_mul_f32_e32 v76, v76, v230
	v_mul_f32_e32 v77, v77, v231
	v_mul_f32_e32 v78, v78, v232
	v_mul_f32_e32 v79, v79, v233
	v_cvt_pk_bf16_f32 v184, v84, v85
	v_cvt_pk_bf16_f32 v185, v86, v87
	v_cvt_pk_bf16_f32 v186, v76, v77
	v_cvt_pk_bf16_f32 v187, v78, v79
	v_lshlrev_b32_e32 v128, 16, v188
	v_and_b32_e32 v129, 0xffff0000, v188
	v_lshlrev_b32_e32 v130, 16, v189
	v_and_b32_e32 v131, 0xffff0000, v189
	v_lshlrev_b32_e32 v230, 16, v190
	v_and_b32_e32 v231, 0xffff0000, v190
	v_lshlrev_b32_e32 v232, 16, v191
	v_and_b32_e32 v233, 0xffff0000, v191
	v_mul_f32_e32 v68, v68, v128
	v_mul_f32_e32 v69, v69, v129
	v_mul_f32_e32 v70, v70, v130
	v_mul_f32_e32 v71, v71, v131
	v_mul_f32_e32 v64, v64, v230
	v_mul_f32_e32 v65, v65, v231
	v_mul_f32_e32 v66, v66, v232
	v_mul_f32_e32 v67, v67, v233
	v_cvt_pk_bf16_f32 v188, v68, v69
	v_cvt_pk_bf16_f32 v189, v70, v71
	v_cvt_pk_bf16_f32 v190, v64, v65
	v_cvt_pk_bf16_f32 v191, v66, v67
	ds_write_b128 v245, v[184:187]
	ds_read_b128 v[184:187], v234
	ds_write_b128 v245, v[188:191]
	ds_read_b128 v[188:191], v234
	s_waitcnt lgkmcnt(2)
	global_store_dwordx4 v243, v[184:187], s[10:11]
	s_waitcnt lgkmcnt(0)
	global_store_dwordx4 v243, v[188:191], s[10:11] offset:256
	v_add_u32_e32 v243, 0x28000, v243
	s_waitcnt vmcnt(14)
	ds_write_b128 v234, v[192:195]
	ds_read_b128 v[192:195], v245
	ds_write_b128 v234, v[196:199]
	ds_read_b128 v[196:199], v245
	s_waitcnt lgkmcnt(0)
	v_lshlrev_b32_e32 v128, 16, v192
	v_and_b32_e32 v129, 0xffff0000, v192
	v_lshlrev_b32_e32 v130, 16, v193
	v_and_b32_e32 v131, 0xffff0000, v193
	v_lshlrev_b32_e32 v230, 16, v194
	v_and_b32_e32 v231, 0xffff0000, v194
	v_lshlrev_b32_e32 v232, 16, v195
	v_and_b32_e32 v233, 0xffff0000, v195
	v_mul_f32_e32 v60, v60, v128
	v_mul_f32_e32 v61, v61, v129
	v_mul_f32_e32 v62, v62, v130
	v_mul_f32_e32 v63, v63, v131
	v_mul_f32_e32 v56, v56, v230
	v_mul_f32_e32 v57, v57, v231
	v_mul_f32_e32 v58, v58, v232
	v_mul_f32_e32 v59, v59, v233
	v_cvt_pk_bf16_f32 v192, v60, v61
	v_cvt_pk_bf16_f32 v193, v62, v63
	v_cvt_pk_bf16_f32 v194, v56, v57
	v_cvt_pk_bf16_f32 v195, v58, v59
	v_lshlrev_b32_e32 v128, 16, v196
	v_and_b32_e32 v129, 0xffff0000, v196
	v_lshlrev_b32_e32 v130, 16, v197
	v_and_b32_e32 v131, 0xffff0000, v197
	v_lshlrev_b32_e32 v230, 16, v198
	v_and_b32_e32 v231, 0xffff0000, v198
	v_lshlrev_b32_e32 v232, 16, v199
	v_and_b32_e32 v233, 0xffff0000, v199
	v_mul_f32_e32 v48, v48, v128
	v_mul_f32_e32 v49, v49, v129
	v_mul_f32_e32 v50, v50, v130
	v_mul_f32_e32 v51, v51, v131
	v_mul_f32_e32 v40, v40, v230
	v_mul_f32_e32 v41, v41, v231
	v_mul_f32_e32 v42, v42, v232
	v_mul_f32_e32 v43, v43, v233
	v_cvt_pk_bf16_f32 v196, v48, v49
	v_cvt_pk_bf16_f32 v197, v50, v51
	v_cvt_pk_bf16_f32 v198, v40, v41
	v_cvt_pk_bf16_f32 v199, v42, v43
	ds_write_b128 v245, v[192:195]
	ds_read_b128 v[192:195], v234
	ds_write_b128 v245, v[196:199]
	ds_read_b128 v[196:199], v234
	s_waitcnt lgkmcnt(2)
	global_store_dwordx4 v243, v[192:195], s[10:11]
	s_waitcnt lgkmcnt(0)
	global_store_dwordx4 v243, v[196:199], s[10:11] offset:256
	v_add_u32_e32 v243, 0x8000, v243
	s_waitcnt vmcnt(14)
; __device__ __forceinline__ void unpack8(const u32x4 w, float (&f)[8]) { f[0] = bflo(w.x); f[1] = bfhi(w.x); f[2] = bflo(w.y); f[3] = bfhi(w.y); f[4] = bflo(w.z); f[5] = bfhi(w.z); f[6] = bflo(w.w); f[7] = bfhi(w.w); }
; __device__ __forceinline__ u32x4 pack8(const float (&f)[8]) { u32x4 w; w.x = cvt_pk_bf16(f[0], f[1]); w.y = cvt_pk_bf16(f[2], f[3]); w.z = cvt_pk_bf16(f[4], f[5]); w.w = cvt_pk_bf16(f[6], f[7]); return w; }
;     __device__ __forceinline__ void operator()(const f32x4 (&acc)[2][2][4][2], const Unit& u, int wr, int wc, int fr, int fq) const {
;         const int row0 = u.pm * BM + wr * 64 + fr, col0 = u.pn * BM + wc * 32 + 8 * fq;
; #pragma unroll
;         for (int ai = 0; ai < 2; ++ai)
; #pragma unroll
;             for (int m = 0; m < 4; ++m) { const size_t idx = (size_t)(row0 + ai * HALF + m * 16) * 1024 + col0;
; #pragma unroll
;                 for (int bj = 0; bj < 2; ++bj) { const f32x4 v0 = acc[ai][bj][m][0], v1 = acc[ai][bj][m][1];
;                     float f[8] = {v0[0], v0[1], v0[2], v0[3], v1[0], v1[1], v1[2], v1[3]}; float g[8];
;                     unpack8(__builtin_nontemporal_load((const u32x4*)(gate + idx + bj * HALF)), g);
; #pragma unroll
;                     for (int e = 0; e < 8; ++e) f[e] *= g[e];
;                     if (!FIRST) { float p[8]; unpack8(*(const u32x4*)(merged + idx + bj * HALF), p);
; #pragma unroll
;                         for (int e = 0; e < 8; ++e) f[e] += p[e]; }
;                     *(u32x4*)(merged + idx + bj * HALF) = pack8(f); } }
	ds_write_b128 v234, v[206:209]
	ds_read_b128 v[206:209], v245
	ds_write_b128 v234, v[210:213]
	ds_read_b128 v[210:213], v245
	s_waitcnt lgkmcnt(0)
	v_lshlrev_b32_e32 v128, 16, v206
	v_and_b32_e32 v129, 0xffff0000, v206
	v_lshlrev_b32_e32 v130, 16, v207
	v_and_b32_e32 v131, 0xffff0000, v207
	v_lshlrev_b32_e32 v230, 16, v208
	v_and_b32_e32 v231, 0xffff0000, v208
	v_lshlrev_b32_e32 v232, 16, v209
	v_and_b32_e32 v233, 0xffff0000, v209
	v_mul_f32_e32 v52, v52, v128
	v_mul_f32_e32 v53, v53, v129
	v_mul_f32_e32 v54, v54, v130
	v_mul_f32_e32 v55, v55, v131
	v_mul_f32_e32 v44, v44, v230
	v_mul_f32_e32 v45, v45, v231
	v_mul_f32_e32 v46, v46, v232
	v_mul_f32_e32 v47, v47, v233
	v_cvt_pk_bf16_f32 v206, v52, v53
	v_cvt_pk_bf16_f32 v207, v54, v55
	v_cvt_pk_bf16_f32 v208, v44, v45
	v_cvt_pk_bf16_f32 v209, v46, v47
	v_lshlrev_b32_e32 v128, 16, v210
	v_and_b32_e32 v129, 0xffff0000, v210
	v_lshlrev_b32_e32 v130, 16, v211
	v_and_b32_e32 v131, 0xffff0000, v211
	v_lshlrev_b32_e32 v230, 16, v212
	v_and_b32_e32 v231, 0xffff0000, v212
	v_lshlrev_b32_e32 v232, 16, v213
	v_and_b32_e32 v233, 0xffff0000, v213
	v_mul_f32_e32 v32, v32, v128
	v_mul_f32_e32 v33, v33, v129
	v_mul_f32_e32 v34, v34, v130
	v_mul_f32_e32 v35, v35, v131
	v_mul_f32_e32 v24, v24, v230
	v_mul_f32_e32 v25, v25, v231
	v_mul_f32_e32 v26, v26, v232
	v_mul_f32_e32 v27, v27, v233
	v_cvt_pk_bf16_f32 v210, v32, v33
	v_cvt_pk_bf16_f32 v211, v34, v35
	v_cvt_pk_bf16_f32 v212, v24, v25
	v_cvt_pk_bf16_f32 v213, v26, v27
	ds_write_b128 v245, v[206:209]
	ds_read_b128 v[206:209], v234
	ds_write_b128 v245, v[210:213]
	ds_read_b128 v[210:213], v234
	s_waitcnt lgkmcnt(2)
	global_store_dwordx4 v243, v[206:209], s[10:11]
	s_waitcnt lgkmcnt(0)
	global_store_dwordx4 v243, v[210:213], s[10:11] offset:256
	v_add_u32_e32 v243, 0x8000, v243
	s_waitcnt vmcnt(14)
	ds_write_b128 v234, v[214:217]
	ds_read_b128 v[214:217], v245
	ds_write_b128 v234, v[218:221]
	ds_read_b128 v[218:221], v245
	s_waitcnt lgkmcnt(0)
	v_lshlrev_b32_e32 v128, 16, v214
	v_and_b32_e32 v129, 0xffff0000, v214
	v_lshlrev_b32_e32 v130, 16, v215
	v_and_b32_e32 v131, 0xffff0000, v215
	v_lshlrev_b32_e32 v230, 16, v216
	v_and_b32_e32 v231, 0xffff0000, v216
	v_lshlrev_b32_e32 v232, 16, v217
	v_and_b32_e32 v233, 0xffff0000, v217
	v_mul_f32_e32 v36, v36, v128
	v_mul_f32_e32 v37, v37, v129
	v_mul_f32_e32 v38, v38, v130
	v_mul_f32_e32 v39, v39, v131
	v_mul_f32_e32 v28, v28, v230
	v_mul_f32_e32 v29, v29, v231
	v_mul_f32_e32 v30, v30, v232
	v_mul_f32_e32 v31, v31, v233
	v_cvt_pk_bf16_f32 v214, v36, v37
	v_cvt_pk_bf16_f32 v215, v38, v39
	v_cvt_pk_bf16_f32 v216, v28, v29
	v_cvt_pk_bf16_f32 v217, v30, v31
	v_lshlrev_b32_e32 v128, 16, v218
	v_and_b32_e32 v129, 0xffff0000, v218
	v_lshlrev_b32_e32 v130, 16, v219
	v_and_b32_e32 v131, 0xffff0000, v219
	v_lshlrev_b32_e32 v230, 16, v220
	v_and_b32_e32 v231, 0xffff0000, v220
	v_lshlrev_b32_e32 v232, 16, v221
	v_and_b32_e32 v233, 0xffff0000, v221
	v_mul_f32_e32 v16, v16, v128
	v_mul_f32_e32 v17, v17, v129
	v_mul_f32_e32 v18, v18, v130
	v_mul_f32_e32 v19, v19, v131
	v_mul_f32_e32 v8, v8, v230
	v_mul_f32_e32 v9, v9, v231
	v_mul_f32_e32 v10, v10, v232
	v_mul_f32_e32 v11, v11, v233
	v_cvt_pk_bf16_f32 v218, v16, v17
	v_cvt_pk_bf16_f32 v219, v18, v19
	v_cvt_pk_bf16_f32 v220, v8, v9
	v_cvt_pk_bf16_f32 v221, v10, v11
	ds_write_b128 v245, v[214:217]
	ds_read_b128 v[214:217], v234
	ds_write_b128 v245, v[218:221]
	ds_read_b128 v[218:221], v234
	s_waitcnt lgkmcnt(2)
	global_store_dwordx4 v243, v[214:217], s[10:11]
	s_waitcnt lgkmcnt(0)
	global_store_dwordx4 v243, v[218:221], s[10:11] offset:256
	v_add_u32_e32 v243, 0x8000, v243
	s_waitcnt vmcnt(14)
	ds_write_b128 v234, v[222:225]
	ds_read_b128 v[222:225], v245
	ds_write_b128 v234, v[226:229]
	ds_read_b128 v[226:229], v245
	s_waitcnt lgkmcnt(0)
	v_lshlrev_b32_e32 v128, 16, v222
	v_and_b32_e32 v129, 0xffff0000, v222
	v_lshlrev_b32_e32 v130, 16, v223
	v_and_b32_e32 v131, 0xffff0000, v223
	v_lshlrev_b32_e32 v230, 16, v224
	v_and_b32_e32 v231, 0xffff0000, v224
	v_lshlrev_b32_e32 v232, 16, v225
	v_and_b32_e32 v233, 0xffff0000, v225
	v_mul_f32_e32 v20, v20, v128
	v_mul_f32_e32 v21, v21, v129
	v_mul_f32_e32 v22, v22, v130
	v_mul_f32_e32 v23, v23, v131
	v_mul_f32_e32 v12, v12, v230
	v_mul_f32_e32 v13, v13, v231
	v_mul_f32_e32 v14, v14, v232
	v_mul_f32_e32 v15, v15, v233
	v_cvt_pk_bf16_f32 v222, v20, v21
	v_cvt_pk_bf16_f32 v223, v22, v23
	v_cvt_pk_bf16_f32 v224, v12, v13
	v_cvt_pk_bf16_f32 v225, v14, v15
	v_lshlrev_b32_e32 v128, 16, v226
	v_and_b32_e32 v129, 0xffff0000, v226
	v_lshlrev_b32_e32 v130, 16, v227
	v_and_b32_e32 v131, 0xffff0000, v227
	v_lshlrev_b32_e32 v230, 16, v228
	v_and_b32_e32 v231, 0xffff0000, v228
	v_lshlrev_b32_e32 v232, 16, v229
	v_and_b32_e32 v233, 0xffff0000, v229
	v_mul_f32_e32 v4, v4, v128
	v_mul_f32_e32 v5, v5, v129
	v_mul_f32_e32 v6, v6, v130
	v_mul_f32_e32 v7, v7, v131
	v_mul_f32_e32 v0, v0, v230
	v_mul_f32_e32 v1, v1, v231
	v_mul_f32_e32 v2, v2, v232
	v_mul_f32_e32 v3, v3, v233
	v_cvt_pk_bf16_f32 v226, v4, v5
	v_cvt_pk_bf16_f32 v227, v6, v7
	v_cvt_pk_bf16_f32 v228, v0, v1
	v_cvt_pk_bf16_f32 v229, v2, v3
	ds_write_b128 v245, v[222:225]
	ds_read_b128 v[222:225], v234
	ds_write_b128 v245, v[226:229]
	ds_read_b128 v[226:229], v234
	s_waitcnt lgkmcnt(2)
	global_store_dwordx4 v243, v[222:225], s[10:11]
	s_waitcnt lgkmcnt(0)
	global_store_dwordx4 v243, v[226:229], s[10:11] offset:256
	s_branch .Lp3_done
; __device__ __forceinline__ void unpack8(const u32x4 w, float (&f)[8]) { f[0] = bflo(w.x); f[1] = bfhi(w.x); f[2] = bflo(w.y); f[3] = bfhi(w.y); f[4] = bflo(w.z); f[5] = bfhi(w.z); f[6] = bflo(w.w); f[7] = bfhi(w.w); }
; __device__ __forceinline__ u32x4 pack8(const float (&f)[8]) { u32x4 w; w.x = cvt_pk_bf16(f[0], f[1]); w.y = cvt_pk_bf16(f[2], f[3]); w.z = cvt_pk_bf16(f[4], f[5]); w.w = cvt_pk_bf16(f[6], f[7]); return w; }
;     __device__ __forceinline__ void operator()(const f32x4 (&acc)[2][2][4][2], const Unit& u, int wr, int wc, int fr, int fq) const {
;         const int row0 = u.pm * BM + wr * 64 + fr, col0 = u.pn * BM + wc * 32 + 8 * fq;
; #pragma unroll
;         for (int ai = 0; ai < 2; ++ai)
; #pragma unroll
;             for (int m = 0; m < 4; ++m) { const size_t idx = (size_t)(row0 + ai * HALF + m * 16) * 1024 + col0;
; #pragma unroll
;                 for (int bj = 0; bj < 2; ++bj) { const f32x4 v0 = acc[ai][bj][m][0], v1 = acc[ai][bj][m][1];
;                     float f[8] = {v0[0], v0[1], v0[2], v0[3], v1[0], v1[1], v1[2], v1[3]}; float g[8];
;                     unpack8(__builtin_nontemporal_load((const u32x4*)(gate + idx + bj * HALF)), g);
; #pragma unroll
;                     for (int e = 0; e < 8; ++e) f[e] *= g[e];
;                     if (!FIRST) { float p[8]; unpack8(*(const u32x4*)(merged + idx + bj * HALF), p);
; #pragma unroll
;                         for (int e = 0; e < 8; ++e) f[e] += p[e]; }
;                     *(u32x4*)(merged + idx + bj * HALF) = pack8(f); } }
.Lp3_second:
	global_load_dwordx4 v[160:163], v244, s[100:101] nt
	global_load_dwordx4 v[164:167], v244, s[100:101] offset:256 nt
	global_load_dwordx4 v[168:171], v242, s[10:11]
	global_load_dwordx4 v[172:175], v242, s[10:11] offset:256
	v_add_u32_e32 v244, 0x8000, v244
	v_add_u32_e32 v242, 0x8000, v242
	global_load_dwordx4 v[176:179], v244, s[100:101] nt
	global_load_dwordx4 v[180:183], v244, s[100:101] offset:256 nt
	global_load_dwordx4 v[184:187], v242, s[10:11]
	global_load_dwordx4 v[188:191], v242, s[10:11] offset:256
	v_add_u32_e32 v244, 0x8000, v244
	v_add_u32_e32 v242, 0x8000, v242
	global_load_dwordx4 v[192:195], v244, s[100:101] nt
	global_load_dwordx4 v[196:199], v244, s[100:101] offset:256 nt
	global_load_dwordx4 v[206:209], v242, s[10:11]
	global_load_dwordx4 v[210:213], v242, s[10:11] offset:256
	v_add_u32_e32 v244, 0x8000, v244
	v_add_u32_e32 v242, 0x8000, v242
	global_load_dwordx4 v[214:217], v244, s[100:101] nt
	global_load_dwordx4 v[218:221], v244, s[100:101] offset:256 nt
	global_load_dwordx4 v[222:225], v242, s[10:11]
	global_load_dwordx4 v[226:229], v242, s[10:11] offset:256
	v_add_u32_e32 v244, 0x28000, v244
	v_add_u32_e32 v242, 0x28000, v242
	s_waitcnt vmcnt(12)
	ds_write_b128 v234, v[160:163]
	ds_read_b128 v[160:163], v245
	ds_write_b128 v234, v[164:167]
	ds_read_b128 v[164:167], v245
	ds_write_b128 v234, v[168:171]
	ds_read_b128 v[168:171], v245
	ds_write_b128 v234, v[172:175]
	ds_read_b128 v[172:175], v245
	s_waitcnt lgkmcnt(0)
	v_lshlrev_b32_e32 v128, 16, v160
	v_and_b32_e32 v129, 0xffff0000, v160
	v_lshlrev_b32_e32 v130, 16, v161
	v_and_b32_e32 v131, 0xffff0000, v161
	v_lshlrev_b32_e32 v230, 16, v162
	v_and_b32_e32 v231, 0xffff0000, v162
	v_lshlrev_b32_e32 v232, 16, v163
	v_and_b32_e32 v233, 0xffff0000, v163
	v_lshlrev_b32_e32 v148, 16, v168
	v_and_b32_e32 v149, 0xffff0000, v168
	v_lshlrev_b32_e32 v150, 16, v169
	v_and_b32_e32 v151, 0xffff0000, v169
	v_lshlrev_b32_e32 v200, 16, v170
	v_and_b32_e32 v201, 0xffff0000, v170
	v_lshlrev_b32_e32 v202, 16, v171
	v_and_b32_e32 v203, 0xffff0000, v171
	v_fmac_f32_e32 v148, v124, v128
	v_fmac_f32_e32 v149, v125, v129
	v_fmac_f32_e32 v150, v126, v130
	v_fmac_f32_e32 v151, v127, v131
	v_fmac_f32_e32 v200, v120, v230
	v_fmac_f32_e32 v201, v121, v231
	v_fmac_f32_e32 v202, v122, v232
	v_fmac_f32_e32 v203, v123, v233
	v_cvt_pk_bf16_f32 v160, v148, v149
	v_cvt_pk_bf16_f32 v161, v150, v151
	v_cvt_pk_bf16_f32 v162, v200, v201
	v_cvt_pk_bf16_f32 v163, v202, v203
	v_lshlrev_b32_e32 v128, 16, v164
	v_and_b32_e32 v129, 0xffff0000, v164
	v_lshlrev_b32_e32 v130, 16, v165
	v_and_b32_e32 v131, 0xffff0000, v165
	v_lshlrev_b32_e32 v230, 16, v166
	v_and_b32_e32 v231, 0xffff0000, v166
	v_lshlrev_b32_e32 v232, 16, v167
	v_and_b32_e32 v233, 0xffff0000, v167
	v_lshlrev_b32_e32 v148, 16, v172
	v_and_b32_e32 v149, 0xffff0000, v172
	v_lshlrev_b32_e32 v150, 16, v173
	v_and_b32_e32 v151, 0xffff0000, v173
	v_lshlrev_b32_e32 v200, 16, v174
	v_and_b32_e32 v201, 0xffff0000, v174
	v_lshlrev_b32_e32 v202, 16, v175
	v_and_b32_e32 v203, 0xffff0000, v175
	v_fmac_f32_e32 v148, v112, v128
	v_fmac_f32_e32 v149, v113, v129
	v_fmac_f32_e32 v150, v114, v130
	v_fmac_f32_e32 v151, v115, v131
	v_fmac_f32_e32 v200, v104, v230
	v_fmac_f32_e32 v201, v105, v231
	v_fmac_f32_e32 v202, v106, v232
	v_fmac_f32_e32 v203, v107, v233
	v_cvt_pk_bf16_f32 v164, v148, v149
	v_cvt_pk_bf16_f32 v165, v150, v151
	v_cvt_pk_bf16_f32 v166, v200, v201
	v_cvt_pk_bf16_f32 v167, v202, v203
	ds_write_b128 v245, v[160:163]
	ds_read_b128 v[160:163], v234
	ds_write_b128 v245, v[164:167]
	ds_read_b128 v[164:167], v234
	s_waitcnt lgkmcnt(2)
	global_store_dwordx4 v243, v[160:163], s[10:11]
	s_waitcnt lgkmcnt(0)
	global_store_dwordx4 v243, v[164:167], s[10:11] offset:256
	v_add_u32_e32 v243, 0x8000, v243
	global_load_dwordx4 v[160:163], v244, s[100:101] nt
	global_load_dwordx4 v[164:167], v244, s[100:101] offset:256 nt
	global_load_dwordx4 v[168:171], v242, s[10:11]
	global_load_dwordx4 v[172:175], v242, s[10:11] offset:256
	v_add_u32_e32 v244, 0x8000, v244
	v_add_u32_e32 v242, 0x8000, v242
	s_waitcnt vmcnt(14)
	ds_write_b128 v234, v[176:179]
	ds_read_b128 v[176:179], v245
	ds_write_b128 v234, v[180:183]
	ds_read_b128 v[180:183], v245
	ds_write_b128 v234, v[184:187]
	ds_read_b128 v[184:187], v245
	ds_write_b128 v234, v[188:191]
	ds_read_b128 v[188:191], v245
	s_waitcnt lgkmcnt(0)
	v_lshlrev_b32_e32 v128, 16, v176
	v_and_b32_e32 v129, 0xffff0000, v176
	v_lshlrev_b32_e32 v130, 16, v177
	v_and_b32_e32 v131, 0xffff0000, v177
	v_lshlrev_b32_e32 v230, 16, v178
	v_and_b32_e32 v231, 0xffff0000, v178
	v_lshlrev_b32_e32 v232, 16, v179
	v_and_b32_e32 v233, 0xffff0000, v179
	v_lshlrev_b32_e32 v148, 16, v184
	v_and_b32_e32 v149, 0xffff0000, v184
	v_lshlrev_b32_e32 v150, 16, v185
	v_and_b32_e32 v151, 0xffff0000, v185
	v_lshlrev_b32_e32 v200, 16, v186
	v_and_b32_e32 v201, 0xffff0000, v186
	v_lshlrev_b32_e32 v202, 16, v187
	v_and_b32_e32 v203, 0xffff0000, v187
	v_fmac_f32_e32 v148, v116, v128
	v_fmac_f32_e32 v149, v117, v129
	v_fmac_f32_e32 v150, v118, v130
	v_fmac_f32_e32 v151, v119, v131
	v_fmac_f32_e32 v200, v108, v230
	v_fmac_f32_e32 v201, v109, v231
	v_fmac_f32_e32 v202, v110, v232
	v_fmac_f32_e32 v203, v111, v233
	v_cvt_pk_bf16_f32 v176, v148, v149
	v_cvt_pk_bf16_f32 v177, v150, v151
	v_cvt_pk_bf16_f32 v178, v200, v201
	v_cvt_pk_bf16_f32 v179, v202, v203
	v_lshlrev_b32_e32 v128, 16, v180
	v_and_b32_e32 v129, 0xffff0000, v180
	v_lshlrev_b32_e32 v130, 16, v181
	v_and_b32_e32 v131, 0xffff0000, v181
	v_lshlrev_b32_e32 v230, 16, v182
	v_and_b32_e32 v231, 0xffff0000, v182
	v_lshlrev_b32_e32 v232, 16, v183
	v_and_b32_e32 v233, 0xffff0000, v183
	v_lshlrev_b32_e32 v148, 16, v188
	v_and_b32_e32 v149, 0xffff0000, v188
	v_lshlrev_b32_e32 v150, 16, v189
	v_and_b32_e32 v151, 0xffff0000, v189
	v_lshlrev_b32_e32 v200, 16, v190
	v_and_b32_e32 v201, 0xffff0000, v190
	v_lshlrev_b32_e32 v202, 16, v191
	v_and_b32_e32 v203, 0xffff0000, v191
	v_fmac_f32_e32 v148, v96, v128
	v_fmac_f32_e32 v149, v97, v129
	v_fmac_f32_e32 v150, v98, v130
	v_fmac_f32_e32 v151, v99, v131
	v_fmac_f32_e32 v200, v88, v230
	v_fmac_f32_e32 v201, v89, v231
	v_fmac_f32_e32 v202, v90, v232
	v_fmac_f32_e32 v203, v91, v233
	v_cvt_pk_bf16_f32 v180, v148, v149
	v_cvt_pk_bf16_f32 v181, v150, v151
	v_cvt_pk_bf16_f32 v182, v200, v201
	v_cvt_pk_bf16_f32 v183, v202, v203
	ds_write_b128 v245, v[176:179]
	ds_read_b128 v[176:179], v234
	ds_write_b128 v245, v[180:183]
	ds_read_b128 v[180:183], v234
	s_waitcnt lgkmcnt(2)
; __device__ __forceinline__ void unpack8(const u32x4 w, float (&f)[8]) { f[0] = bflo(w.x); f[1] = bfhi(w.x); f[2] = bflo(w.y); f[3] = bfhi(w.y); f[4] = bflo(w.z); f[5] = bfhi(w.z); f[6] = bflo(w.w); f[7] = bfhi(w.w); }
; __device__ __forceinline__ u32x4 pack8(const float (&f)[8]) { u32x4 w; w.x = cvt_pk_bf16(f[0], f[1]); w.y = cvt_pk_bf16(f[2], f[3]); w.z = cvt_pk_bf16(f[4], f[5]); w.w = cvt_pk_bf16(f[6], f[7]); return w; }
;     __device__ __forceinline__ void operator()(const f32x4 (&acc)[2][2][4][2], const Unit& u, int wr, int wc, int fr, int fq) const {
;     ...
;             for (int m = 0; m < 4; ++m) { const size_t idx = (size_t)(row0 + ai * HALF + m * 16) * 1024 + col0;
; #pragma unroll
;                 for (int bj = 0; bj < 2; ++bj) { const f32x4 v0 = acc[ai][bj][m][0], v1 = acc[ai][bj][m][1];
;                     float f[8] = {v0[0], v0[1], v0[2], v0[3], v1[0], v1[1], v1[2], v1[3]}; float g[8];
;                     unpack8(__builtin_nontemporal_load((const u32x4*)(gate + idx + bj * HALF)), g);
; #pragma unroll
;                     for (int e = 0; e < 8; ++e) f[e] *= g[e];
;                     if (!FIRST) { float p[8]; unpack8(*(const u32x4*)(merged + idx + bj * HALF), p);
; #pragma unroll
;                         for (int e = 0; e < 8; ++e) f[e] += p[e]; }
;                     *(u32x4*)(merged + idx + bj * HALF) = pack8(f); } }
	global_store_dwordx4 v243, v[176:179], s[10:11]
	s_waitcnt lgkmcnt(0)
	global_store_dwordx4 v243, v[180:183], s[10:11] offset:256
	v_add_u32_e32 v243, 0x8000, v243
	global_load_dwordx4 v[176:179], v244, s[100:101] nt
	global_load_dwordx4 v[180:183], v244, s[100:101] offset:256 nt
	global_load_dwordx4 v[184:187], v242, s[10:11]
	global_load_dwordx4 v[188:191], v242, s[10:11] offset:256
	v_add_u32_e32 v244, 0x8000, v244
	v_add_u32_e32 v242, 0x8000, v242
	s_waitcnt vmcnt(16)
	ds_write_b128 v234, v[192:195]
	ds_read_b128 v[192:195], v245
	ds_write_b128 v234, v[196:199]
	ds_read_b128 v[196:199], v245
	ds_write_b128 v234, v[206:209]
	ds_read_b128 v[206:209], v245
	ds_write_b128 v234, v[210:213]
	ds_read_b128 v[210:213], v245
	s_waitcnt lgkmcnt(0)
	v_lshlrev_b32_e32 v128, 16, v192
	v_and_b32_e32 v129, 0xffff0000, v192
	v_lshlrev_b32_e32 v130, 16, v193
	v_and_b32_e32 v131, 0xffff0000, v193
	v_lshlrev_b32_e32 v230, 16, v194
	v_and_b32_e32 v231, 0xffff0000, v194
	v_lshlrev_b32_e32 v232, 16, v195
	v_and_b32_e32 v233, 0xffff0000, v195
	v_lshlrev_b32_e32 v148, 16, v206
	v_and_b32_e32 v149, 0xffff0000, v206
	v_lshlrev_b32_e32 v150, 16, v207
	v_and_b32_e32 v151, 0xffff0000, v207
	v_lshlrev_b32_e32 v200, 16, v208
	v_and_b32_e32 v201, 0xffff0000, v208
	v_lshlrev_b32_e32 v202, 16, v209
	v_and_b32_e32 v203, 0xffff0000, v209
	v_fmac_f32_e32 v148, v100, v128
	v_fmac_f32_e32 v149, v101, v129
	v_fmac_f32_e32 v150, v102, v130
	v_fmac_f32_e32 v151, v103, v131
	v_fmac_f32_e32 v200, v92, v230
	v_fmac_f32_e32 v201, v93, v231
	v_fmac_f32_e32 v202, v94, v232
	v_fmac_f32_e32 v203, v95, v233
	v_cvt_pk_bf16_f32 v192, v148, v149
	v_cvt_pk_bf16_f32 v193, v150, v151
	v_cvt_pk_bf16_f32 v194, v200, v201
	v_cvt_pk_bf16_f32 v195, v202, v203
	v_lshlrev_b32_e32 v128, 16, v196
	v_and_b32_e32 v129, 0xffff0000, v196
	v_lshlrev_b32_e32 v130, 16, v197
	v_and_b32_e32 v131, 0xffff0000, v197
	v_lshlrev_b32_e32 v230, 16, v198
	v_and_b32_e32 v231, 0xffff0000, v198
	v_lshlrev_b32_e32 v232, 16, v199
	v_and_b32_e32 v233, 0xffff0000, v199
	v_lshlrev_b32_e32 v148, 16, v210
	v_and_b32_e32 v149, 0xffff0000, v210
	v_lshlrev_b32_e32 v150, 16, v211
	v_and_b32_e32 v151, 0xffff0000, v211
	v_lshlrev_b32_e32 v200, 16, v212
	v_and_b32_e32 v201, 0xffff0000, v212
	v_lshlrev_b32_e32 v202, 16, v213
	v_and_b32_e32 v203, 0xffff0000, v213
	v_fmac_f32_e32 v148, v80, v128
	v_fmac_f32_e32 v149, v81, v129
	v_fmac_f32_e32 v150, v82, v130
	v_fmac_f32_e32 v151, v83, v131
	v_fmac_f32_e32 v200, v72, v230
	v_fmac_f32_e32 v201, v73, v231
	v_fmac_f32_e32 v202, v74, v232
	v_fmac_f32_e32 v203, v75, v233
	v_cvt_pk_bf16_f32 v196, v148, v149
	v_cvt_pk_bf16_f32 v197, v150, v151
	v_cvt_pk_bf16_f32 v198, v200, v201
	v_cvt_pk_bf16_f32 v199, v202, v203
	ds_write_b128 v245, v[192:195]
	ds_read_b128 v[192:195], v234
	ds_write_b128 v245, v[196:199]
	ds_read_b128 v[196:199], v234
	s_waitcnt lgkmcnt(2)
	global_store_dwordx4 v243, v[192:195], s[10:11]
	s_waitcnt lgkmcnt(0)
	global_store_dwordx4 v243, v[196:199], s[10:11] offset:256
	v_add_u32_e32 v243, 0x8000, v243
	global_load_dwordx4 v[192:195], v244, s[100:101] nt
	global_load_dwordx4 v[196:199], v244, s[100:101] offset:256 nt
	global_load_dwordx4 v[206:209], v242, s[10:11]
	global_load_dwordx4 v[210:213], v242, s[10:11] offset:256
	v_add_u32_e32 v244, 0x8000, v244
	v_add_u32_e32 v242, 0x8000, v242
	s_waitcnt vmcnt(18)
	ds_write_b128 v234, v[214:217]
	ds_read_b128 v[214:217], v245
	ds_write_b128 v234, v[218:221]
	ds_read_b128 v[218:221], v245
	ds_write_b128 v234, v[222:225]
	ds_read_b128 v[222:225], v245
	ds_write_b128 v234, v[226:229]
	ds_read_b128 v[226:229], v245
	s_waitcnt lgkmcnt(0)
	v_lshlrev_b32_e32 v128, 16, v214
	v_and_b32_e32 v129, 0xffff0000, v214
	v_lshlrev_b32_e32 v130, 16, v215
	v_and_b32_e32 v131, 0xffff0000, v215
	v_lshlrev_b32_e32 v230, 16, v216
	v_and_b32_e32 v231, 0xffff0000, v216
	v_lshlrev_b32_e32 v232, 16, v217
	v_and_b32_e32 v233, 0xffff0000, v217
	v_lshlrev_b32_e32 v148, 16, v222
	v_and_b32_e32 v149, 0xffff0000, v222
	v_lshlrev_b32_e32 v150, 16, v223
	v_and_b32_e32 v151, 0xffff0000, v223
	v_lshlrev_b32_e32 v200, 16, v224
	v_and_b32_e32 v201, 0xffff0000, v224
	v_lshlrev_b32_e32 v202, 16, v225
	v_and_b32_e32 v203, 0xffff0000, v225
	v_fmac_f32_e32 v148, v84, v128
	v_fmac_f32_e32 v149, v85, v129
	v_fmac_f32_e32 v150, v86, v130
	v_fmac_f32_e32 v151, v87, v131
	v_fmac_f32_e32 v200, v76, v230
	v_fmac_f32_e32 v201, v77, v231
	v_fmac_f32_e32 v202, v78, v232
	v_fmac_f32_e32 v203, v79, v233
	v_cvt_pk_bf16_f32 v214, v148, v149
	v_cvt_pk_bf16_f32 v215, v150, v151
	v_cvt_pk_bf16_f32 v216, v200, v201
	v_cvt_pk_bf16_f32 v217, v202, v203
	v_lshlrev_b32_e32 v128, 16, v218
	v_and_b32_e32 v129, 0xffff0000, v218
	v_lshlrev_b32_e32 v130, 16, v219
	v_and_b32_e32 v131, 0xffff0000, v219
	v_lshlrev_b32_e32 v230, 16, v220
	v_and_b32_e32 v231, 0xffff0000, v220
	v_lshlrev_b32_e32 v232, 16, v221
	v_and_b32_e32 v233, 0xffff0000, v221
	v_lshlrev_b32_e32 v148, 16, v226
	v_and_b32_e32 v149, 0xffff0000, v226
	v_lshlrev_b32_e32 v150, 16, v227
	v_and_b32_e32 v151, 0xffff0000, v227
	v_lshlrev_b32_e32 v200, 16, v228
	v_and_b32_e32 v201, 0xffff0000, v228
	v_lshlrev_b32_e32 v202, 16, v229
	v_and_b32_e32 v203, 0xffff0000, v229
	v_fmac_f32_e32 v148, v68, v128
	v_fmac_f32_e32 v149, v69, v129
	v_fmac_f32_e32 v150, v70, v130
	v_fmac_f32_e32 v151, v71, v131
	v_fmac_f32_e32 v200, v64, v230
	v_fmac_f32_e32 v201, v65, v231
	v_fmac_f32_e32 v202, v66, v232
	v_fmac_f32_e32 v203, v67, v233
	v_cvt_pk_bf16_f32 v218, v148, v149
	v_cvt_pk_bf16_f32 v219, v150, v151
	v_cvt_pk_bf16_f32 v220, v200, v201
	v_cvt_pk_bf16_f32 v221, v202, v203
	ds_write_b128 v245, v[214:217]
	ds_read_b128 v[214:217], v234
	ds_write_b128 v245, v[218:221]
	ds_read_b128 v[218:221], v234
	s_waitcnt lgkmcnt(2)
; __device__ __forceinline__ void unpack8(const u32x4 w, float (&f)[8]) { f[0] = bflo(w.x); f[1] = bfhi(w.x); f[2] = bflo(w.y); f[3] = bfhi(w.y); f[4] = bflo(w.z); f[5] = bfhi(w.z); f[6] = bflo(w.w); f[7] = bfhi(w.w); }
; __device__ __forceinline__ u32x4 pack8(const float (&f)[8]) { u32x4 w; w.x = cvt_pk_bf16(f[0], f[1]); w.y = cvt_pk_bf16(f[2], f[3]); w.z = cvt_pk_bf16(f[4], f[5]); w.w = cvt_pk_bf16(f[6], f[7]); return w; }
;     __device__ __forceinline__ void operator()(const f32x4 (&acc)[2][2][4][2], const Unit& u, int wr, int wc, int fr, int fq) const {
;     ...
;             for (int m = 0; m < 4; ++m) { const size_t idx = (size_t)(row0 + ai * HALF + m * 16) * 1024 + col0;
; #pragma unroll
;                 for (int bj = 0; bj < 2; ++bj) { const f32x4 v0 = acc[ai][bj][m][0], v1 = acc[ai][bj][m][1];
;                     float f[8] = {v0[0], v0[1], v0[2], v0[3], v1[0], v1[1], v1[2], v1[3]}; float g[8];
;                     unpack8(__builtin_nontemporal_load((const u32x4*)(gate + idx + bj * HALF)), g);
; #pragma unroll
;                     for (int e = 0; e < 8; ++e) f[e] *= g[e];
;                     if (!FIRST) { float p[8]; unpack8(*(const u32x4*)(merged + idx + bj * HALF), p);
; #pragma unroll
;                         for (int e = 0; e < 8; ++e) f[e] += p[e]; }
;                     *(u32x4*)(merged + idx + bj * HALF) = pack8(f); } }
	global_store_dwordx4 v243, v[214:217], s[10:11]
	s_waitcnt lgkmcnt(0)
	global_store_dwordx4 v243, v[218:221], s[10:11] offset:256
	v_add_u32_e32 v243, 0x28000, v243
	global_load_dwordx4 v[214:217], v244, s[100:101] nt
	global_load_dwordx4 v[218:221], v244, s[100:101] offset:256 nt
	global_load_dwordx4 v[222:225], v242, s[10:11]
	global_load_dwordx4 v[226:229], v242, s[10:11] offset:256
	s_waitcnt vmcnt(18)
	ds_write_b128 v234, v[160:163]
	ds_read_b128 v[160:163], v245
	ds_write_b128 v234, v[164:167]
	ds_read_b128 v[164:167], v245
	ds_write_b128 v234, v[168:171]
	ds_read_b128 v[168:171], v245
	ds_write_b128 v234, v[172:175]
	ds_read_b128 v[172:175], v245
	s_waitcnt lgkmcnt(0)
	v_lshlrev_b32_e32 v128, 16, v160
	v_and_b32_e32 v129, 0xffff0000, v160
	v_lshlrev_b32_e32 v130, 16, v161
	v_and_b32_e32 v131, 0xffff0000, v161
	v_lshlrev_b32_e32 v230, 16, v162
	v_and_b32_e32 v231, 0xffff0000, v162
	v_lshlrev_b32_e32 v232, 16, v163
	v_and_b32_e32 v233, 0xffff0000, v163
	v_lshlrev_b32_e32 v148, 16, v168
	v_and_b32_e32 v149, 0xffff0000, v168
	v_lshlrev_b32_e32 v150, 16, v169
	v_and_b32_e32 v151, 0xffff0000, v169
	v_lshlrev_b32_e32 v200, 16, v170
	v_and_b32_e32 v201, 0xffff0000, v170
	v_lshlrev_b32_e32 v202, 16, v171
	v_and_b32_e32 v203, 0xffff0000, v171
	v_fmac_f32_e32 v148, v60, v128
	v_fmac_f32_e32 v149, v61, v129
	v_fmac_f32_e32 v150, v62, v130
	v_fmac_f32_e32 v151, v63, v131
	v_fmac_f32_e32 v200, v56, v230
	v_fmac_f32_e32 v201, v57, v231
	v_fmac_f32_e32 v202, v58, v232
	v_fmac_f32_e32 v203, v59, v233
	v_cvt_pk_bf16_f32 v160, v148, v149
	v_cvt_pk_bf16_f32 v161, v150, v151
	v_cvt_pk_bf16_f32 v162, v200, v201
	v_cvt_pk_bf16_f32 v163, v202, v203
	v_lshlrev_b32_e32 v128, 16, v164
	v_and_b32_e32 v129, 0xffff0000, v164
	v_lshlrev_b32_e32 v130, 16, v165
	v_and_b32_e32 v131, 0xffff0000, v165
	v_lshlrev_b32_e32 v230, 16, v166
	v_and_b32_e32 v231, 0xffff0000, v166
	v_lshlrev_b32_e32 v232, 16, v167
	v_and_b32_e32 v233, 0xffff0000, v167
	v_lshlrev_b32_e32 v148, 16, v172
	v_and_b32_e32 v149, 0xffff0000, v172
	v_lshlrev_b32_e32 v150, 16, v173
	v_and_b32_e32 v151, 0xffff0000, v173
	v_lshlrev_b32_e32 v200, 16, v174
	v_and_b32_e32 v201, 0xffff0000, v174
	v_lshlrev_b32_e32 v202, 16, v175
	v_and_b32_e32 v203, 0xffff0000, v175
	v_fmac_f32_e32 v148, v48, v128
	v_fmac_f32_e32 v149, v49, v129
	v_fmac_f32_e32 v150, v50, v130
	v_fmac_f32_e32 v151, v51, v131
	v_fmac_f32_e32 v200, v40, v230
	v_fmac_f32_e32 v201, v41, v231
	v_fmac_f32_e32 v202, v42, v232
	v_fmac_f32_e32 v203, v43, v233
	v_cvt_pk_bf16_f32 v164, v148, v149
	v_cvt_pk_bf16_f32 v165, v150, v151
	v_cvt_pk_bf16_f32 v166, v200, v201
	v_cvt_pk_bf16_f32 v167, v202, v203
	ds_write_b128 v245, v[160:163]
	ds_read_b128 v[160:163], v234
	ds_write_b128 v245, v[164:167]
	ds_read_b128 v[164:167], v234
	s_waitcnt lgkmcnt(2)
	global_store_dwordx4 v243, v[160:163], s[10:11]
	s_waitcnt lgkmcnt(0)
	global_store_dwordx4 v243, v[164:167], s[10:11] offset:256
	v_add_u32_e32 v243, 0x8000, v243
	s_waitcnt vmcnt(14)
	ds_write_b128 v234, v[176:179]
	ds_read_b128 v[176:179], v245
	ds_write_b128 v234, v[180:183]
	ds_read_b128 v[180:183], v245
	ds_write_b128 v234, v[184:187]
	ds_read_b128 v[184:187], v245
	ds_write_b128 v234, v[188:191]
	ds_read_b128 v[188:191], v245
	s_waitcnt lgkmcnt(0)
	v_lshlrev_b32_e32 v128, 16, v176
	v_and_b32_e32 v129, 0xffff0000, v176
	v_lshlrev_b32_e32 v130, 16, v177
	v_and_b32_e32 v131, 0xffff0000, v177
	v_lshlrev_b32_e32 v230, 16, v178
	v_and_b32_e32 v231, 0xffff0000, v178
	v_lshlrev_b32_e32 v232, 16, v179
	v_and_b32_e32 v233, 0xffff0000, v179
	v_lshlrev_b32_e32 v148, 16, v184
	v_and_b32_e32 v149, 0xffff0000, v184
	v_lshlrev_b32_e32 v150, 16, v185
	v_and_b32_e32 v151, 0xffff0000, v185
	v_lshlrev_b32_e32 v200, 16, v186
	v_and_b32_e32 v201, 0xffff0000, v186
	v_lshlrev_b32_e32 v202, 16, v187
	v_and_b32_e32 v203, 0xffff0000, v187
	v_fmac_f32_e32 v148, v52, v128
	v_fmac_f32_e32 v149, v53, v129
	v_fmac_f32_e32 v150, v54, v130
	v_fmac_f32_e32 v151, v55, v131
	v_fmac_f32_e32 v200, v44, v230
	v_fmac_f32_e32 v201, v45, v231
	v_fmac_f32_e32 v202, v46, v232
	v_fmac_f32_e32 v203, v47, v233
	v_cvt_pk_bf16_f32 v176, v148, v149
	v_cvt_pk_bf16_f32 v177, v150, v151
	v_cvt_pk_bf16_f32 v178, v200, v201
	v_cvt_pk_bf16_f32 v179, v202, v203
	v_lshlrev_b32_e32 v128, 16, v180
	v_and_b32_e32 v129, 0xffff0000, v180
	v_lshlrev_b32_e32 v130, 16, v181
	v_and_b32_e32 v131, 0xffff0000, v181
	v_lshlrev_b32_e32 v230, 16, v182
	v_and_b32_e32 v231, 0xffff0000, v182
	v_lshlrev_b32_e32 v232, 16, v183
	v_and_b32_e32 v233, 0xffff0000, v183
	v_lshlrev_b32_e32 v148, 16, v188
	v_and_b32_e32 v149, 0xffff0000, v188
	v_lshlrev_b32_e32 v150, 16, v189
	v_and_b32_e32 v151, 0xffff0000, v189
	v_lshlrev_b32_e32 v200, 16, v190
	v_and_b32_e32 v201, 0xffff0000, v190
	v_lshlrev_b32_e32 v202, 16, v191
	v_and_b32_e32 v203, 0xffff0000, v191
	v_fmac_f32_e32 v148, v32, v128
	v_fmac_f32_e32 v149, v33, v129
	v_fmac_f32_e32 v150, v34, v130
	v_fmac_f32_e32 v151, v35, v131
	v_fmac_f32_e32 v200, v24, v230
	v_fmac_f32_e32 v201, v25, v231
	v_fmac_f32_e32 v202, v26, v232
	v_fmac_f32_e32 v203, v27, v233
	v_cvt_pk_bf16_f32 v180, v148, v149
	v_cvt_pk_bf16_f32 v181, v150, v151
	v_cvt_pk_bf16_f32 v182, v200, v201
	v_cvt_pk_bf16_f32 v183, v202, v203
	ds_write_b128 v245, v[176:179]
	ds_read_b128 v[176:179], v234
	ds_write_b128 v245, v[180:183]
	ds_read_b128 v[180:183], v234
	s_waitcnt lgkmcnt(2)
; __device__ __forceinline__ void unpack8(const u32x4 w, float (&f)[8]) { f[0] = bflo(w.x); f[1] = bfhi(w.x); f[2] = bflo(w.y); f[3] = bfhi(w.y); f[4] = bflo(w.z); f[5] = bfhi(w.z); f[6] = bflo(w.w); f[7] = bfhi(w.w); }
; __device__ __forceinline__ u32x4 pack8(const float (&f)[8]) { u32x4 w; w.x = cvt_pk_bf16(f[0], f[1]); w.y = cvt_pk_bf16(f[2], f[3]); w.z = cvt_pk_bf16(f[4], f[5]); w.w = cvt_pk_bf16(f[6], f[7]); return w; }
;     __device__ __forceinline__ void operator()(const f32x4 (&acc)[2][2][4][2], const Unit& u, int wr, int wc, int fr, int fq) const {
;     ...
;             for (int m = 0; m < 4; ++m) { const size_t idx = (size_t)(row0 + ai * HALF + m * 16) * 1024 + col0;
; #pragma unroll
;                 for (int bj = 0; bj < 2; ++bj) { const f32x4 v0 = acc[ai][bj][m][0], v1 = acc[ai][bj][m][1];
;                     float f[8] = {v0[0], v0[1], v0[2], v0[3], v1[0], v1[1], v1[2], v1[3]}; float g[8];
;                     unpack8(__builtin_nontemporal_load((const u32x4*)(gate + idx + bj * HALF)), g);
; #pragma unroll
;                     for (int e = 0; e < 8; ++e) f[e] *= g[e];
;                     if (!FIRST) { float p[8]; unpack8(*(const u32x4*)(merged + idx + bj * HALF), p);
; #pragma unroll
;                         for (int e = 0; e < 8; ++e) f[e] += p[e]; }
;                     *(u32x4*)(merged + idx + bj * HALF) = pack8(f); } }
	global_store_dwordx4 v243, v[176:179], s[10:11]
	s_waitcnt lgkmcnt(0)
	global_store_dwordx4 v243, v[180:183], s[10:11] offset:256
	v_add_u32_e32 v243, 0x8000, v243
	s_waitcnt vmcnt(10)
	ds_write_b128 v234, v[192:195]
	ds_read_b128 v[192:195], v245
	ds_write_b128 v234, v[196:199]
	ds_read_b128 v[196:199], v245
	ds_write_b128 v234, v[206:209]
	ds_read_b128 v[206:209], v245
	ds_write_b128 v234, v[210:213]
	ds_read_b128 v[210:213], v245
	s_waitcnt lgkmcnt(0)
	v_lshlrev_b32_e32 v128, 16, v192
	v_and_b32_e32 v129, 0xffff0000, v192
	v_lshlrev_b32_e32 v130, 16, v193
	v_and_b32_e32 v131, 0xffff0000, v193
	v_lshlrev_b32_e32 v230, 16, v194
	v_and_b32_e32 v231, 0xffff0000, v194
	v_lshlrev_b32_e32 v232, 16, v195
	v_and_b32_e32 v233, 0xffff0000, v195
	v_lshlrev_b32_e32 v148, 16, v206
	v_and_b32_e32 v149, 0xffff0000, v206
	v_lshlrev_b32_e32 v150, 16, v207
	v_and_b32_e32 v151, 0xffff0000, v207
	v_lshlrev_b32_e32 v200, 16, v208
	v_and_b32_e32 v201, 0xffff0000, v208
	v_lshlrev_b32_e32 v202, 16, v209
	v_and_b32_e32 v203, 0xffff0000, v209
	v_fmac_f32_e32 v148, v36, v128
	v_fmac_f32_e32 v149, v37, v129
	v_fmac_f32_e32 v150, v38, v130
	v_fmac_f32_e32 v151, v39, v131
	v_fmac_f32_e32 v200, v28, v230
	v_fmac_f32_e32 v201, v29, v231
	v_fmac_f32_e32 v202, v30, v232
	v_fmac_f32_e32 v203, v31, v233
	v_cvt_pk_bf16_f32 v192, v148, v149
	v_cvt_pk_bf16_f32 v193, v150, v151
	v_cvt_pk_bf16_f32 v194, v200, v201
	v_cvt_pk_bf16_f32 v195, v202, v203
	v_lshlrev_b32_e32 v128, 16, v196
	v_and_b32_e32 v129, 0xffff0000, v196
	v_lshlrev_b32_e32 v130, 16, v197
	v_and_b32_e32 v131, 0xffff0000, v197
	v_lshlrev_b32_e32 v230, 16, v198
	v_and_b32_e32 v231, 0xffff0000, v198
	v_lshlrev_b32_e32 v232, 16, v199
	v_and_b32_e32 v233, 0xffff0000, v199
	v_lshlrev_b32_e32 v148, 16, v210
	v_and_b32_e32 v149, 0xffff0000, v210
	v_lshlrev_b32_e32 v150, 16, v211
	v_and_b32_e32 v151, 0xffff0000, v211
	v_lshlrev_b32_e32 v200, 16, v212
	v_and_b32_e32 v201, 0xffff0000, v212
	v_lshlrev_b32_e32 v202, 16, v213
	v_and_b32_e32 v203, 0xffff0000, v213
	v_fmac_f32_e32 v148, v16, v128
	v_fmac_f32_e32 v149, v17, v129
	v_fmac_f32_e32 v150, v18, v130
	v_fmac_f32_e32 v151, v19, v131
	v_fmac_f32_e32 v200, v8, v230
	v_fmac_f32_e32 v201, v9, v231
	v_fmac_f32_e32 v202, v10, v232
	v_fmac_f32_e32 v203, v11, v233
	v_cvt_pk_bf16_f32 v196, v148, v149
	v_cvt_pk_bf16_f32 v197, v150, v151
	v_cvt_pk_bf16_f32 v198, v200, v201
	v_cvt_pk_bf16_f32 v199, v202, v203
	ds_write_b128 v245, v[192:195]
	ds_read_b128 v[192:195], v234
	ds_write_b128 v245, v[196:199]
	ds_read_b128 v[196:199], v234
	s_waitcnt lgkmcnt(2)
	global_store_dwordx4 v243, v[192:195], s[10:11]
	s_waitcnt lgkmcnt(0)
	global_store_dwordx4 v243, v[196:199], s[10:11] offset:256
	v_add_u32_e32 v243, 0x8000, v243
	s_waitcnt vmcnt(6)
	ds_write_b128 v234, v[214:217]
	ds_read_b128 v[214:217], v245
	ds_write_b128 v234, v[218:221]
	ds_read_b128 v[218:221], v245
	ds_write_b128 v234, v[222:225]
	ds_read_b128 v[222:225], v245
	ds_write_b128 v234, v[226:229]
	ds_read_b128 v[226:229], v245
	s_waitcnt lgkmcnt(0)
	v_lshlrev_b32_e32 v128, 16, v214
	v_and_b32_e32 v129, 0xffff0000, v214
	v_lshlrev_b32_e32 v130, 16, v215
	v_and_b32_e32 v131, 0xffff0000, v215
	v_lshlrev_b32_e32 v230, 16, v216
	v_and_b32_e32 v231, 0xffff0000, v216
	v_lshlrev_b32_e32 v232, 16, v217
	v_and_b32_e32 v233, 0xffff0000, v217
	v_lshlrev_b32_e32 v148, 16, v222
	v_and_b32_e32 v149, 0xffff0000, v222
	v_lshlrev_b32_e32 v150, 16, v223
	v_and_b32_e32 v151, 0xffff0000, v223
	v_lshlrev_b32_e32 v200, 16, v224
	v_and_b32_e32 v201, 0xffff0000, v224
	v_lshlrev_b32_e32 v202, 16, v225
	v_and_b32_e32 v203, 0xffff0000, v225
	v_fmac_f32_e32 v148, v20, v128
	v_fmac_f32_e32 v149, v21, v129
	v_fmac_f32_e32 v150, v22, v130
	v_fmac_f32_e32 v151, v23, v131
	v_fmac_f32_e32 v200, v12, v230
	v_fmac_f32_e32 v201, v13, v231
	v_fmac_f32_e32 v202, v14, v232
	v_fmac_f32_e32 v203, v15, v233
	v_cvt_pk_bf16_f32 v214, v148, v149
	v_cvt_pk_bf16_f32 v215, v150, v151
	v_cvt_pk_bf16_f32 v216, v200, v201
	v_cvt_pk_bf16_f32 v217, v202, v203
	v_lshlrev_b32_e32 v128, 16, v218
	v_and_b32_e32 v129, 0xffff0000, v218
	v_lshlrev_b32_e32 v130, 16, v219
	v_and_b32_e32 v131, 0xffff0000, v219
	v_lshlrev_b32_e32 v230, 16, v220
	v_and_b32_e32 v231, 0xffff0000, v220
	v_lshlrev_b32_e32 v232, 16, v221
	v_and_b32_e32 v233, 0xffff0000, v221
	v_lshlrev_b32_e32 v148, 16, v226
	v_and_b32_e32 v149, 0xffff0000, v226
	v_lshlrev_b32_e32 v150, 16, v227
	v_and_b32_e32 v151, 0xffff0000, v227
	v_lshlrev_b32_e32 v200, 16, v228
	v_and_b32_e32 v201, 0xffff0000, v228
	v_lshlrev_b32_e32 v202, 16, v229
	v_and_b32_e32 v203, 0xffff0000, v229
	v_fmac_f32_e32 v148, v4, v128
	v_fmac_f32_e32 v149, v5, v129
	v_fmac_f32_e32 v150, v6, v130
	v_fmac_f32_e32 v151, v7, v131
	v_fmac_f32_e32 v200, v0, v230
	v_fmac_f32_e32 v201, v1, v231
	v_fmac_f32_e32 v202, v2, v232
	v_fmac_f32_e32 v203, v3, v233
	v_cvt_pk_bf16_f32 v218, v148, v149
	v_cvt_pk_bf16_f32 v219, v150, v151
	v_cvt_pk_bf16_f32 v220, v200, v201
	v_cvt_pk_bf16_f32 v221, v202, v203
	ds_write_b128 v245, v[214:217]
	ds_read_b128 v[214:217], v234
	ds_write_b128 v245, v[218:221]
	ds_read_b128 v[218:221], v234
	s_waitcnt lgkmcnt(2)
	global_store_dwordx4 v243, v[214:217], s[10:11]
	s_waitcnt lgkmcnt(0)
	global_store_dwordx4 v243, v[218:221], s[10:11] offset:256
